# POST transposing blocks: the four row loads of each block issued together (counted waits) instead of load-wait-write four times
# speedup vs baseline: 1.0042x; 1.0014x over previous
; #define LAS __attribute__((address_space(3)))
; __device__ __forceinline__ int perm16(int row) { const int q = (row >> 2) & 3; const int q2 = (q == 1) ? 2 : (q == 2 ? 1 : q); return (row & ~15) | (q2 << 2) | (row & 3); }
; template <bool PERMK, class F> __device__ __forceinline__ void post_transpose(const bf16_t* px, int c0, LAS unsigned short* Lt, int tid, F&& destrow) {
;     u32x4 v[4];
; #pragma unroll
;     for (int j = 0; j < 4; ++j) { const int c = tid + j * NTHREADS; v[j] = *(const u32x4*)(px + (size_t)(c >> 4) * NIN + c0 + (c & 15) * 8); }
; #pragma unroll
;     for (int j = 0; j < 4; ++j) {
;         const int c = tid + j * NTHREADS, row = c >> 4, ch = c & 15;
;         const int pr = (PERMK ? perm16(row) : row) ^ (ch << 3);
;         LAS unsigned short* d = Lt + (ch * 8) * 136 + pr;
;         d[0] = (unsigned short)(v[j].x & 0xffff); d[136] = (unsigned short)(v[j].x >> 16); d[2 * 136] = (unsigned short)(v[j].y & 0xffff); d[3 * 136] = (unsigned short)(v[j].y >> 16);
;         d[4 * 136] = (unsigned short)(v[j].z & 0xffff); d[5 * 136] = (unsigned short)(v[j].z >> 16); d[6 * 136] = (unsigned short)(v[j].w & 0xffff); d[7 * 136] = (unsigned short)(v[j].w >> 16);
;     }
;     __syncthreads();
; #pragma unroll
;     for (int j = 0; j < 4; ++j) {
;         const int c = tid + j * NTHREADS, col = c >> 4, ch = c & 15;
;         const u32x4 w = *(const LAS u32x4*)(Lt + col * 136 + ((ch * 8) ^ (((col >> 3) & 15) << 3)));
;         *(u32x4*)(destrow(col) + ch * 8) = w;
;     }
.LBB0_360:
	s_and_b64 vcc, exec, s[0:1]
	s_cbranch_vccz .LBB0_377
	v_lshlrev_b32_e32 v186, 1, v48
	v_lshl_add_u64 v[8:9], s[46:47], 0, v[186:187]
	v_lshl_add_u64 v[14:15], v[8:9], 0, v[50:51]
	global_load_dwordx4 v[16:19], v[14:15], off offset:1536
	v_lshl_add_u64 v[12:13], v[8:9], 0, v[52:53]
	v_lshl_add_u64 v[10:11], v[8:9], 0, v[54:55]
	v_lshl_add_u64 v[8:9], v[8:9], 0, v[56:57]
	global_load_dwordx4 v[160:163], v[12:13], off offset:1536
	global_load_dwordx4 v[164:167], v[10:11], off offset:1536
	global_load_dwordx4 v[168:171], v[8:9], off offset:1536
	s_lshl_b32 s76, s9, 1
	s_lshl_b32 s10, s8, 8
	v_lshl_add_u64 v[6:7], v[60:61], 0, s[76:77]
	v_lshl_add_u64 v[4:5], v[64:65], 0, s[76:77]
	v_lshl_add_u64 v[2:3], v[68:69], 0, s[76:77]
	v_lshl_add_u64 v[0:1], v[72:73], 0, s[76:77]
	s_mov_b64 s[0:1], -1
	s_and_b64 vcc, exec, s[94:95]
	s_waitcnt vmcnt(3)
	ds_write_b16 v67, v16
	ds_write_b16_d16_hi v67, v16 offset:272
	ds_write_b16 v67, v17 offset:544
	ds_write_b16_d16_hi v67, v17 offset:816
	ds_write_b16 v67, v18 offset:1088
	ds_write_b16_d16_hi v67, v18 offset:1360
	ds_write_b16 v67, v19 offset:1632
	ds_write_b16_d16_hi v67, v19 offset:1904
	s_waitcnt vmcnt(2)
	ds_write_b16 v71, v160
	ds_write_b16_d16_hi v71, v160 offset:272
	ds_write_b16 v71, v161 offset:544
	ds_write_b16_d16_hi v71, v161 offset:816
	ds_write_b16 v71, v162 offset:1088
	ds_write_b16_d16_hi v71, v162 offset:1360
	ds_write_b16 v71, v163 offset:1632
	ds_write_b16_d16_hi v71, v163 offset:1904
	s_waitcnt vmcnt(1)
	ds_write_b16 v77, v164
	ds_write_b16_d16_hi v77, v164 offset:272
	ds_write_b16 v77, v165 offset:544
	ds_write_b16_d16_hi v77, v165 offset:816
	ds_write_b16 v77, v166 offset:1088
	ds_write_b16_d16_hi v77, v166 offset:1360
	ds_write_b16 v77, v167 offset:1632
	ds_write_b16_d16_hi v77, v167 offset:1904
	s_waitcnt vmcnt(0)
	ds_write_b16 v106, v168
	ds_write_b16_d16_hi v106, v168 offset:272
	ds_write_b16 v106, v169 offset:544
	ds_write_b16_d16_hi v106, v169 offset:816
	ds_write_b16 v106, v170 offset:1088
	ds_write_b16_d16_hi v106, v170 offset:1360
	ds_write_b16 v106, v171 offset:1632
	ds_write_b16_d16_hi v106, v171 offset:1904
	s_waitcnt lgkmcnt(0)
	s_cbranch_vccz .LBB0_363
	s_barrier
	ds_read_b128 v[16:19], v107
	v_or_b32_e32 v186, s10, v58
	v_lshlrev_b64 v[20:21], 10, v[186:187]
	v_lshl_add_u64 v[20:21], v[6:7], 0, v[20:21]
	v_or_b32_e32 v186, s10, v62
	s_waitcnt lgkmcnt(0)
	global_store_dwordx4 v[20:21], v[16:19], off
	ds_read_b128 v[16:19], v108
	v_lshlrev_b64 v[20:21], 10, v[186:187]
	v_lshl_add_u64 v[20:21], v[4:5], 0, v[20:21]
	v_or_b32_e32 v186, s10, v66
	s_mov_b64 s[0:1], 0
	s_waitcnt lgkmcnt(0)
	global_store_dwordx4 v[20:21], v[16:19], off
	ds_read_b128 v[16:19], v109
	v_lshlrev_b64 v[20:21], 10, v[186:187]
	v_lshl_add_u64 v[20:21], v[2:3], 0, v[20:21]
	v_or_b32_e32 v186, s10, v70
	s_waitcnt lgkmcnt(0)
	global_store_dwordx4 v[20:21], v[16:19], off
	ds_read_b128 v[16:19], v110
	v_lshlrev_b64 v[20:21], 10, v[186:187]
	v_lshl_add_u64 v[20:21], v[0:1], 0, v[20:21]
	s_waitcnt lgkmcnt(0)
	global_store_dwordx4 v[20:21], v[16:19], off
	s_barrier

; #define LAS __attribute__((address_space(3)))
; __device__ __forceinline__ int perm16(int row) { const int q = (row >> 2) & 3; const int q2 = (q == 1) ? 2 : (q == 2 ? 1 : q); return (row & ~15) | (q2 << 2) | (row & 3); }
; template <bool PERMK, class F> __device__ __forceinline__ void post_transpose(const bf16_t* px, int c0, LAS unsigned short* Lt, int tid, F&& destrow) {
;     u32x4 v[4];
; #pragma unroll
;     for (int j = 0; j < 4; ++j) { const int c = tid + j * NTHREADS; v[j] = *(const u32x4*)(px + (size_t)(c >> 4) * NIN + c0 + (c & 15) * 8); }
; #pragma unroll
;     for (int j = 0; j < 4; ++j) {
;         const int c = tid + j * NTHREADS, row = c >> 4, ch = c & 15;
;         const int pr = (PERMK ? perm16(row) : row) ^ (ch << 3);
;         LAS unsigned short* d = Lt + (ch * 8) * 136 + pr;
;         d[0] = (unsigned short)(v[j].x & 0xffff); d[136] = (unsigned short)(v[j].x >> 16); d[2 * 136] = (unsigned short)(v[j].y & 0xffff); d[3 * 136] = (unsigned short)(v[j].y >> 16);
;         d[4 * 136] = (unsigned short)(v[j].z & 0xffff); d[5 * 136] = (unsigned short)(v[j].z >> 16); d[6 * 136] = (unsigned short)(v[j].w & 0xffff); d[7 * 136] = (unsigned short)(v[j].w >> 16);
;     }
;     __syncthreads();
; #pragma unroll
;     for (int j = 0; j < 4; ++j) {
;         const int c = tid + j * NTHREADS, col = c >> 4, ch = c & 15;
;         const u32x4 w = *(const LAS u32x4*)(Lt + col * 136 + ((ch * 8) ^ (((col >> 3) & 15) << 3)));
;         *(u32x4*)(destrow(col) + ch * 8) = w;
;     }
.LBB0_365:
	global_load_dwordx4 v[26:29], v[14:15], off offset:1792
	global_load_dwordx4 v[160:163], v[12:13], off offset:1792
	global_load_dwordx4 v[164:167], v[10:11], off offset:1792
	global_load_dwordx4 v[168:171], v[8:9], off offset:1792
	v_cndmask_b32_e64 v19, 0, 1, s[94:95]
	s_mov_b64 s[4:5], -1
	v_cmp_ne_u32_e64 s[0:1], 1, v19
	s_andn2_b64 vcc, exec, s[94:95]
	s_waitcnt vmcnt(3)
	ds_write_b16 v67, v26
	ds_write_b16_d16_hi v67, v26 offset:272
	ds_write_b16 v67, v27 offset:544
	ds_write_b16_d16_hi v67, v27 offset:816
	ds_write_b16 v67, v28 offset:1088
	ds_write_b16_d16_hi v67, v28 offset:1360
	ds_write_b16 v67, v29 offset:1632
	ds_write_b16_d16_hi v67, v29 offset:1904
	s_waitcnt vmcnt(2)
	ds_write_b16 v71, v160
	ds_write_b16_d16_hi v71, v160 offset:272
	ds_write_b16 v71, v161 offset:544
	ds_write_b16_d16_hi v71, v161 offset:816
	ds_write_b16 v71, v162 offset:1088
	ds_write_b16_d16_hi v71, v162 offset:1360
	ds_write_b16 v71, v163 offset:1632
	ds_write_b16_d16_hi v71, v163 offset:1904
	s_waitcnt vmcnt(1)
	ds_write_b16 v77, v164
	ds_write_b16_d16_hi v77, v164 offset:272
	ds_write_b16 v77, v165 offset:544
	ds_write_b16_d16_hi v77, v165 offset:816
	ds_write_b16 v77, v166 offset:1088
	ds_write_b16_d16_hi v77, v166 offset:1360
	ds_write_b16 v77, v167 offset:1632
	ds_write_b16_d16_hi v77, v167 offset:1904
	s_waitcnt vmcnt(0)
	ds_write_b16 v106, v168
	ds_write_b16_d16_hi v106, v168 offset:272
	ds_write_b16 v106, v169 offset:544
	ds_write_b16_d16_hi v106, v169 offset:816
	ds_write_b16 v106, v170 offset:1088
	ds_write_b16_d16_hi v106, v170 offset:1360
	ds_write_b16 v106, v171 offset:1632
	ds_write_b16_d16_hi v106, v171 offset:1904
	s_waitcnt lgkmcnt(0)
	s_cbranch_vccnz .LBB0_367
	s_barrier
	ds_read_b128 v[26:29], v107
	s_or_b32 s4, s10, 64
	v_or_b32_e32 v186, s4, v58
	v_lshlrev_b64 v[30:31], 10, v[186:187]
	v_lshl_add_u64 v[30:31], v[6:7], 0, v[30:31]
	s_waitcnt lgkmcnt(0)
	global_store_dwordx4 v[30:31], v[26:29], off
	ds_read_b128 v[26:29], v108
	v_or_b32_e32 v186, s4, v62
	v_lshlrev_b64 v[30:31], 10, v[186:187]
	v_lshl_add_u64 v[30:31], v[4:5], 0, v[30:31]
	v_or_b32_e32 v186, s4, v66
	s_waitcnt lgkmcnt(0)
	global_store_dwordx4 v[30:31], v[26:29], off
	ds_read_b128 v[26:29], v109
	v_lshlrev_b64 v[30:31], 10, v[186:187]
	v_lshl_add_u64 v[30:31], v[2:3], 0, v[30:31]
	v_or_b32_e32 v186, s4, v70
	s_mov_b64 s[4:5], 0
	s_waitcnt lgkmcnt(0)
	global_store_dwordx4 v[30:31], v[26:29], off
	ds_read_b128 v[26:29], v110
	v_lshlrev_b64 v[30:31], 10, v[186:187]
	v_lshl_add_u64 v[30:31], v[0:1], 0, v[30:31]
	s_waitcnt lgkmcnt(0)
	global_store_dwordx4 v[30:31], v[26:29], off
	s_barrier

; #define LAS __attribute__((address_space(3)))
; __device__ __forceinline__ int perm16(int row) { const int q = (row >> 2) & 3; const int q2 = (q == 1) ? 2 : (q == 2 ? 1 : q); return (row & ~15) | (q2 << 2) | (row & 3); }
; template <bool PERMK, class F> __device__ __forceinline__ void post_transpose(const bf16_t* px, int c0, LAS unsigned short* Lt, int tid, F&& destrow) {
;     u32x4 v[4];
; #pragma unroll
;     for (int j = 0; j < 4; ++j) { const int c = tid + j * NTHREADS; v[j] = *(const u32x4*)(px + (size_t)(c >> 4) * NIN + c0 + (c & 15) * 8); }
; #pragma unroll
;     for (int j = 0; j < 4; ++j) {
;         const int c = tid + j * NTHREADS, row = c >> 4, ch = c & 15;
;         const int pr = (PERMK ? perm16(row) : row) ^ (ch << 3);
;         LAS unsigned short* d = Lt + (ch * 8) * 136 + pr;
;         d[0] = (unsigned short)(v[j].x & 0xffff); d[136] = (unsigned short)(v[j].x >> 16); d[2 * 136] = (unsigned short)(v[j].y & 0xffff); d[3 * 136] = (unsigned short)(v[j].y >> 16);
;         d[4 * 136] = (unsigned short)(v[j].z & 0xffff); d[5 * 136] = (unsigned short)(v[j].z >> 16); d[6 * 136] = (unsigned short)(v[j].w & 0xffff); d[7 * 136] = (unsigned short)(v[j].w >> 16);
;     }
;     __syncthreads();
; #pragma unroll
;     for (int j = 0; j < 4; ++j) {
;         const int c = tid + j * NTHREADS, col = c >> 4, ch = c & 15;
;         const u32x4 w = *(const LAS u32x4*)(Lt + col * 136 + ((ch * 8) ^ (((col >> 3) & 15) << 3)));
;         *(u32x4*)(destrow(col) + ch * 8) = w;
;     }
.LBB0_369:
	global_load_dwordx4 v[26:29], v[14:15], off offset:2048
	global_load_dwordx4 v[160:163], v[12:13], off offset:2048
	global_load_dwordx4 v[164:167], v[10:11], off offset:2048
	global_load_dwordx4 v[168:171], v[8:9], off offset:2048
	s_mov_b64 s[4:5], -1
	s_and_b64 vcc, exec, s[0:1]
	s_waitcnt vmcnt(3)
	ds_write_b16 v67, v26
	ds_write_b16_d16_hi v67, v26 offset:272
	ds_write_b16 v67, v27 offset:544
	ds_write_b16_d16_hi v67, v27 offset:816
	ds_write_b16 v67, v28 offset:1088
	ds_write_b16_d16_hi v67, v28 offset:1360
	ds_write_b16 v67, v29 offset:1632
	ds_write_b16_d16_hi v67, v29 offset:1904
	s_waitcnt vmcnt(2)
	ds_write_b16 v71, v160
	ds_write_b16_d16_hi v71, v160 offset:272
	ds_write_b16 v71, v161 offset:544
	ds_write_b16_d16_hi v71, v161 offset:816
	ds_write_b16 v71, v162 offset:1088
	ds_write_b16_d16_hi v71, v162 offset:1360
	ds_write_b16 v71, v163 offset:1632
	ds_write_b16_d16_hi v71, v163 offset:1904
	s_waitcnt vmcnt(1)
	ds_write_b16 v77, v164
	ds_write_b16_d16_hi v77, v164 offset:272
	ds_write_b16 v77, v165 offset:544
	ds_write_b16_d16_hi v77, v165 offset:816
	ds_write_b16 v77, v166 offset:1088
	ds_write_b16_d16_hi v77, v166 offset:1360
	ds_write_b16 v77, v167 offset:1632
	ds_write_b16_d16_hi v77, v167 offset:1904
	s_waitcnt vmcnt(0)
	ds_write_b16 v106, v168
	ds_write_b16_d16_hi v106, v168 offset:272
	ds_write_b16 v106, v169 offset:544
	ds_write_b16_d16_hi v106, v169 offset:816
	ds_write_b16 v106, v170 offset:1088
	ds_write_b16_d16_hi v106, v170 offset:1360
	ds_write_b16 v106, v171 offset:1632
	ds_write_b16_d16_hi v106, v171 offset:1904
	s_waitcnt lgkmcnt(0)
	s_cbranch_vccnz .LBB0_371
	s_barrier
	ds_read_b128 v[26:29], v107
	s_or_b32 s4, s10, 0x80
	v_or_b32_e32 v186, s4, v58
	v_lshlrev_b64 v[30:31], 10, v[186:187]
	v_lshl_add_u64 v[30:31], v[6:7], 0, v[30:31]
	s_waitcnt lgkmcnt(0)
	global_store_dwordx4 v[30:31], v[26:29], off
	ds_read_b128 v[26:29], v108
	v_or_b32_e32 v186, s4, v62
	v_lshlrev_b64 v[30:31], 10, v[186:187]
	v_lshl_add_u64 v[30:31], v[4:5], 0, v[30:31]
	v_or_b32_e32 v186, s4, v66
	s_waitcnt lgkmcnt(0)
	global_store_dwordx4 v[30:31], v[26:29], off
	ds_read_b128 v[26:29], v109
	v_lshlrev_b64 v[30:31], 10, v[186:187]
	v_lshl_add_u64 v[30:31], v[2:3], 0, v[30:31]
	v_or_b32_e32 v186, s4, v70
	s_mov_b64 s[4:5], 0
	s_waitcnt lgkmcnt(0)
	global_store_dwordx4 v[30:31], v[26:29], off
	ds_read_b128 v[26:29], v110
	v_lshlrev_b64 v[30:31], 10, v[186:187]
	v_lshl_add_u64 v[30:31], v[0:1], 0, v[30:31]
	s_waitcnt lgkmcnt(0)
	global_store_dwordx4 v[30:31], v[26:29], off
	s_barrier
